# v60 + peephole: adjacent scalar v_mul_f32/v_add_f32 pairs in the ffn_in and GLU epilogues packed into v_pk_mul_f32/v_pk_add_f32 (bit-identical)
# speedup vs baseline: 1.0075x; 1.0075x over previous
; __device__ __forceinline__ unsigned pk2(float lo, float hi) { const f32x2 v = {lo, hi}; const bf16x2_hw b = __builtin_convertvector(v, bf16x2_hw); return __builtin_bit_cast(unsigned, b); }
; __device__ __forceinline__ void unpack8(const u32x4 w, float (&v)[8]) { v[0] = bflo(w.x); v[1] = bfhi(w.x); v[2] = bflo(w.y); v[3] = bfhi(w.y); v[4] = bflo(w.z); v[5] = bfhi(w.z); v[6] = bflo(w.w); v[7] = bfhi(w.w); }
; __device__ __forceinline__ u32x4 pack8(const float (&v)[8]) { u32x4 w; w.x = pk2(v[0], v[1]); w.y = pk2(v[2], v[3]); w.z = pk2(v[4], v[5]); w.w = pk2(v[6], v[7]); return w; }
; __device__ __forceinline__ float sigmoidf_(float x) { return __builtin_amdgcn_rcpf(1.0f + __builtin_amdgcn_exp2f(-LOG2E * x)); }
;     __device__ __forceinline__ bool operator()(Acc& acc, const Unit& u, int wr, int wc, int fr, int fq, const LAS float*) const {
;         const size_t o0 = (size_t)(u.pm * BM + wr * 64 + fr) * 512 + u.pn * BM + wc * 32 + 8 * fq; const bf16_t* yp = YS + o0; bf16_t* zp = Z + o0;
;         u32x4 yv[2][4][2];
; #pragma unroll
;         for (int ai = 0; ai < 2; ++ai)
; #pragma unroll
;             for (int m = 0; m < 4; ++m)
; #pragma unroll
;                 for (int bj = 0; bj < 2; ++bj) yv[ai][m][bj] = gld<u32x4>(yp + (ai * HALF + m * 16) * 512 + bj * HALF);
; #pragma unroll
;         for (int ai = 0; ai < 2; ++ai) {
; #pragma unroll
;             for (int m = 0; m < 4; ++m)
; #pragma unroll
;                 for (int bj = 0; bj < 2; ++bj) {
;                     float y[8]; unpack8(yv[ai][m][bj], y);
;                     float v[8];
; #pragma unroll
;                     for (int e = 0; e < 4; ++e) { v[e] = y[e] * sigmoidf_(acc[ai][bj][m][0][e]); v[4 + e] = y[4 + e] * sigmoidf_(acc[ai][bj][m][1][e]); }
;                     gst<u32x4>(zp + (ai * HALF + m * 16) * 512 + bj * HALF, pack8(v));
;                 }
;             asm volatile("" ::: "memory");
;         }
.LBB0_705:
	v_mov_b32_e32 v34, v1
	s_lshl_b32 s8, s21, 8
	v_mbcnt_lo_u32_b32 v34, -1, v34
	v_readlane_b32 s9, v250, 1
	v_mbcnt_hi_u32_b32 v36, -1, v34
	s_add_i32 s8, s8, s9
	v_and_or_b32 v34, v36, 15, s8
	v_ashrrev_i32_e32 v35, 31, v34
	s_lshl_b32 s8, s20, 8
	v_lshlrev_b64 v[34:35], 9, v[34:35]
	s_ashr_i32 s9, s8, 31
	v_lshl_add_u64 v[34:35], v[34:35], 0, s[8:9]
	v_lshrrev_b32_e32 v36, 1, v36
	v_and_or_b32 v34, v36, 24, v34
	v_readlane_b32 s8, v254, 32
	v_mul_f32_e32 v178, 0xbfb8aa3b, v178
	v_mul_f32_e32 v179, 0xbfb8aa3b, v179
	v_or_b32_e32 v34, s8, v34
	v_lshlrev_b64 v[194:195], 1, v[34:35]
	v_lshl_add_u64 v[34:35], s[22:23], 0, v[194:195]
	global_load_dwordx4 v[190:193], v[34:35], off
	global_load_dwordx4 v[186:189], v[34:35], off offset:256
	s_movk_i32 s8, 0x4000
	v_add_co_u32_e32 v36, vcc, s8, v34
	v_exp_f32_e32 v178, v178
	s_nop 0
	v_addc_co_u32_e32 v37, vcc, 0, v35, vcc
	global_load_dwordx4 v[182:185], v[36:37], off
	global_load_dwordx4 v[174:177], v[36:37], off offset:256
	v_mul_f32_e32 v170, 0xbfb8aa3b, v170
	v_exp_f32_e32 v179, v179
	v_mul_f32_e32 v171, 0xbfb8aa3b, v171
	v_mul_f32_e32 v180, 0xbfb8aa3b, v180
	v_mul_f32_e32 v181, 0xbfb8aa3b, v181
	v_exp_f32_e32 v170, v170
	v_exp_f32_e32 v171, v171
	v_exp_f32_e32 v180, v180
	v_exp_f32_e32 v181, v181
	v_mul_f32_e32 v162, 0xbfb8aa3b, v162
	v_mul_f32_e32 v163, 0xbfb8aa3b, v163
	v_exp_f32_e32 v162, v162
	v_mul_f32_e32 v158, 0xbfb8aa3b, v158
	v_exp_f32_e32 v163, v163
	v_mul_f32_e32 v159, 0xbfb8aa3b, v159
	v_pk_add_f32 v[178:179], v[178:179], 1.0 op_sel_hi:[1,0]
	v_exp_f32_e32 v158, v158
	v_exp_f32_e32 v159, v159
	v_rcp_f32_e32 v178, v178
	v_add_f32_e32 v170, 1.0, v170
	v_rcp_f32_e32 v179, v179
	v_add_f32_e32 v171, 1.0, v171
	v_pk_add_f32 v[180:181], v[180:181], 1.0 op_sel_hi:[1,0]
	v_readlane_b32 s14, v254, 55
	v_rcp_f32_e32 v170, v170
	v_rcp_f32_e32 v171, v171
	v_rcp_f32_e32 v180, v180
	v_rcp_f32_e32 v181, v181
	v_readlane_b32 s15, v254, 56
	v_pk_add_f32 v[162:163], v[162:163], 1.0 op_sel_hi:[1,0]
	v_lshl_add_u64 v[212:213], s[14:15], 0, v[194:195]
	v_rcp_f32_e32 v162, v162
	v_add_f32_e32 v158, 1.0, v158
	v_rcp_f32_e32 v163, v163
	v_add_f32_e32 v159, 1.0, v159
	v_rcp_f32_e32 v158, v158
	v_rcp_f32_e32 v159, v159
	s_mov_b32 s9, 0x8000
	v_add_co_u32_e32 v36, vcc, s9, v34
	v_mul_f32_e32 v172, 0xbfb8aa3b, v172
	s_nop 0
	v_addc_co_u32_e32 v37, vcc, 0, v35, vcc
	global_load_dwordx4 v[166:169], v[36:37], off
	global_load_dwordx4 v[154:157], v[36:37], off offset:256
	v_mul_f32_e32 v173, 0xbfb8aa3b, v173
	v_exp_f32_e32 v172, v172
	v_exp_f32_e32 v173, v173
	s_mov_b32 s10, 0xc000
	v_add_co_u32_e32 v36, vcc, s10, v34
	v_mul_f32_e32 v150, 0xbfb8aa3b, v150
	s_nop 0
	v_addc_co_u32_e32 v37, vcc, 0, v35, vcc
	v_mul_f32_e32 v151, 0xbfb8aa3b, v151
	global_load_dwordx4 v[142:145], v[36:37], off
	global_load_dwordx4 v[130:133], v[36:37], off offset:256
	v_add_co_u32_e32 v36, vcc, s79, v34
	v_pk_add_f32 v[172:173], v[172:173], 1.0 op_sel_hi:[1,0]
	v_exp_f32_e32 v150, v150
	v_mul_f32_e32 v146, 0xbfb8aa3b, v146
	v_exp_f32_e32 v151, v151
	v_mul_f32_e32 v147, 0xbfb8aa3b, v147
	v_addc_co_u32_e32 v37, vcc, 0, v35, vcc
	s_mov_b32 s11, 0x24000
	v_rcp_f32_e32 v172, v172
	v_rcp_f32_e32 v173, v173
	s_waitcnt vmcnt(7)
	v_lshlrev_b32_e32 v194, 16, v190
	v_and_b32_e32 v195, 0xffff0000, v190
	v_pk_mul_f32 v[178:179], v[178:179], v[194:195]
	v_lshlrev_b32_e32 v194, 16, v192
	v_and_b32_e32 v195, 0xffff0000, v192
	v_lshlrev_b32_e32 v190, 16, v191
	v_and_b32_e32 v191, 0xffff0000, v191
	v_pk_mul_f32 v[170:171], v[170:171], v[194:195]
	v_pk_mul_f32 v[180:181], v[180:181], v[190:191]
	v_cvt_pk_bf16_f32 v178, v178, v179
	v_cvt_pk_bf16_f32 v179, v180, v181
	v_cvt_pk_bf16_f32 v180, v170, v171
	s_waitcnt vmcnt(6)
	v_lshlrev_b32_e32 v170, 16, v186
	v_and_b32_e32 v171, 0xffff0000, v186
	v_pk_mul_f32 v[162:163], v[162:163], v[170:171]
	v_lshlrev_b32_e32 v170, 16, v188
	v_and_b32_e32 v171, 0xffff0000, v188
	v_pk_mul_f32 v[170:171], v[158:159], v[170:171]
	v_mul_f32_e32 v159, 0xbfb8aa3b, v160
	v_exp_f32_e32 v159, v159
	v_mul_f32_e32 v158, 0xbfb8aa3b, v164
	v_exp_f32_e32 v158, v158
	v_lshlrev_b32_e32 v164, 16, v187
	v_add_f32_e32 v159, 1.0, v159
	v_rcp_f32_e32 v160, v159
	v_mul_f32_e32 v159, 0xbfb8aa3b, v165
	v_exp_f32_e32 v159, v159
	v_add_f32_e32 v158, 1.0, v158
	v_rcp_f32_e32 v158, v158
	v_and_b32_e32 v165, 0xffff0000, v187
	v_add_f32_e32 v159, 1.0, v159
	v_rcp_f32_e32 v159, v159
	v_exp_f32_e32 v146, v146
	v_exp_f32_e32 v147, v147
	global_load_dwordx4 v[118:121], v[36:37], off
	global_load_dwordx4 v[106:109], v[36:37], off offset:256
	v_pk_mul_f32 v[164:165], v[158:159], v[164:165]
	v_mul_f32_e32 v158, 0xbfb8aa3b, v161
	v_exp_f32_e32 v158, v158
	v_add_co_u32_e32 v36, vcc, s11, v34
	s_mov_b32 s12, 0x28000
	v_add_f32_e32 v158, 1.0, v158
	v_rcp_f32_e32 v161, v158
	v_addc_co_u32_e32 v37, vcc, 0, v35, vcc
	global_load_dwordx4 v[94:97], v[36:37], off
	global_load_dwordx4 v[82:85], v[36:37], off offset:256
	v_add_co_u32_e32 v36, vcc, s12, v34
	v_lshlrev_b32_e32 v190, 16, v193
	v_and_b32_e32 v191, 0xffff0000, v193
	v_pk_add_f32 v[150:151], v[150:151], 1.0 op_sel_hi:[1,0]
	v_addc_co_u32_e32 v37, vcc, 0, v35, vcc
	s_mov_b32 s13, 0x2c000
	v_pk_mul_f32 v[172:173], v[172:173], v[190:191]
	v_lshlrev_b32_e32 v158, 16, v189
	v_and_b32_e32 v159, 0xffff0000, v189
	v_rcp_f32_e32 v150, v150
	v_add_f32_e32 v146, 1.0, v146
	v_rcp_f32_e32 v151, v151
	v_add_f32_e32 v147, 1.0, v147
	v_add_co_u32_e32 v34, vcc, s13, v34
	v_cvt_pk_bf16_f32 v181, v172, v173
	v_pk_mul_f32 v[172:173], v[160:161], v[158:159]
	v_rcp_f32_e32 v146, v146
	v_rcp_f32_e32 v147, v147
	v_addc_co_u32_e32 v35, vcc, 0, v35, vcc
	v_cvt_pk_bf16_f32 v158, v162, v163
	v_cvt_pk_bf16_f32 v159, v164, v165
	v_cvt_pk_bf16_f32 v160, v170, v171
	v_cvt_pk_bf16_f32 v161, v172, v173
	global_load_dwordx4 v[70:73], v[36:37], off
	global_load_dwordx4 v[58:61], v[36:37], off offset:256
	global_load_dwordx4 v[46:49], v[34:35], off
	s_nop 0
	global_load_dwordx4 v[34:37], v[34:35], off offset:256
	v_mul_f32_e32 v138, 0xbfb8aa3b, v138
	global_store_dwordx4 v[212:213], v[158:161], off offset:256
	v_mul_f32_e32 v139, 0xbfb8aa3b, v139
	v_exp_f32_e32 v138, v138
	s_waitcnt vmcnt(14)
; __device__ __forceinline__ unsigned pk2(float lo, float hi) { const f32x2 v = {lo, hi}; const bf16x2_hw b = __builtin_convertvector(v, bf16x2_hw); return __builtin_bit_cast(unsigned, b); }
; __device__ __forceinline__ void unpack8(const u32x4 w, float (&v)[8]) { v[0] = bflo(w.x); v[1] = bfhi(w.x); v[2] = bflo(w.y); v[3] = bfhi(w.y); v[4] = bflo(w.z); v[5] = bfhi(w.z); v[6] = bflo(w.w); v[7] = bfhi(w.w); }
; __device__ __forceinline__ u32x4 pack8(const float (&v)[8]) { u32x4 w; w.x = pk2(v[0], v[1]); w.y = pk2(v[2], v[3]); w.z = pk2(v[4], v[5]); w.w = pk2(v[6], v[7]); return w; }
; __device__ __forceinline__ float sigmoidf_(float x) { return __builtin_amdgcn_rcpf(1.0f + __builtin_amdgcn_exp2f(-LOG2E * x)); }
;     __device__ __forceinline__ bool operator()(Acc& acc, const Unit& u, int wr, int wc, int fr, int fq, const LAS float*) const {
;     ...
; #pragma unroll
;         for (int ai = 0; ai < 2; ++ai) {
; #pragma unroll
;             for (int m = 0; m < 4; ++m)
; #pragma unroll
;                 for (int bj = 0; bj < 2; ++bj) {
;                     float y[8]; unpack8(yv[ai][m][bj], y);
;                     float v[8];
; #pragma unroll
;                     for (int e = 0; e < 4; ++e) { v[e] = y[e] * sigmoidf_(acc[ai][bj][m][0][e]); v[4 + e] = y[4 + e] * sigmoidf_(acc[ai][bj][m][1][e]); }
;                     gst<u32x4>(zp + (ai * HALF + m * 16) * 512 + bj * HALF, pack8(v));
;                 }
;             asm volatile("" ::: "memory");
;         }
	v_lshlrev_b32_e32 v158, 16, v182
	v_and_b32_e32 v159, 0xffff0000, v182
	v_pk_mul_f32 v[150:151], v[150:151], v[158:159]
	v_lshlrev_b32_e32 v158, 16, v184
	v_and_b32_e32 v159, 0xffff0000, v184
	v_pk_mul_f32 v[158:159], v[146:147], v[158:159]
	v_mul_f32_e32 v147, 0xbfb8aa3b, v148
	v_exp_f32_e32 v147, v147
	v_mul_f32_e32 v146, 0xbfb8aa3b, v152
	v_exp_f32_e32 v146, v146
	v_lshlrev_b32_e32 v152, 16, v183
	v_add_f32_e32 v147, 1.0, v147
	v_rcp_f32_e32 v148, v147
	v_mul_f32_e32 v147, 0xbfb8aa3b, v153
	v_exp_f32_e32 v147, v147
	v_add_f32_e32 v146, 1.0, v146
	v_rcp_f32_e32 v146, v146
	v_and_b32_e32 v153, 0xffff0000, v183
	v_add_f32_e32 v147, 1.0, v147
	v_rcp_f32_e32 v147, v147
	v_mul_f32_e32 v134, 0xbfb8aa3b, v134
	v_exp_f32_e32 v139, v139
	v_mul_f32_e32 v135, 0xbfb8aa3b, v135
	v_pk_mul_f32 v[152:153], v[146:147], v[152:153]
	v_mul_f32_e32 v146, 0xbfb8aa3b, v149
	v_exp_f32_e32 v146, v146
	v_exp_f32_e32 v134, v134
	v_exp_f32_e32 v135, v135
	v_add_f32_e32 v138, 1.0, v138
	v_add_f32_e32 v146, 1.0, v146
	v_rcp_f32_e32 v149, v146
	v_add_f32_e32 v139, 1.0, v139
	v_lshlrev_b32_e32 v146, 16, v185
	v_and_b32_e32 v147, 0xffff0000, v185
	v_rcp_f32_e32 v138, v138
	v_add_f32_e32 v134, 1.0, v134
	v_rcp_f32_e32 v139, v139
	v_add_f32_e32 v135, 1.0, v135
	v_pk_mul_f32 v[160:161], v[148:149], v[146:147]
	v_cvt_pk_bf16_f32 v146, v150, v151
	v_add_co_u32_e32 v150, vcc, s8, v212
	v_rcp_f32_e32 v134, v134
	v_rcp_f32_e32 v135, v135
	v_cvt_pk_bf16_f32 v147, v152, v153
	v_cvt_pk_bf16_f32 v148, v158, v159
	v_cvt_pk_bf16_f32 v149, v160, v161
	v_addc_co_u32_e32 v151, vcc, 0, v213, vcc
	global_store_dwordx4 v[150:151], v[146:149], off
	v_mul_f32_e32 v126, 0xbfb8aa3b, v126
	v_mul_f32_e32 v127, 0xbfb8aa3b, v127
	s_waitcnt vmcnt(14)
	v_lshlrev_b32_e32 v146, 16, v174
	v_and_b32_e32 v147, 0xffff0000, v174
	v_pk_mul_f32 v[138:139], v[138:139], v[146:147]
	v_lshlrev_b32_e32 v146, 16, v176
	v_and_b32_e32 v147, 0xffff0000, v176
	v_pk_mul_f32 v[146:147], v[134:135], v[146:147]
	v_mul_f32_e32 v135, 0xbfb8aa3b, v136
	v_exp_f32_e32 v135, v135
	v_mul_f32_e32 v134, 0xbfb8aa3b, v140
	v_exp_f32_e32 v134, v134
	v_lshlrev_b32_e32 v140, 16, v175
	v_add_f32_e32 v135, 1.0, v135
	v_rcp_f32_e32 v136, v135
	v_mul_f32_e32 v135, 0xbfb8aa3b, v141
	v_exp_f32_e32 v135, v135
	v_add_f32_e32 v134, 1.0, v134
	v_rcp_f32_e32 v134, v134
	v_and_b32_e32 v141, 0xffff0000, v175
	v_add_f32_e32 v135, 1.0, v135
	v_rcp_f32_e32 v135, v135
	v_exp_f32_e32 v126, v126
	v_mul_f32_e32 v122, 0xbfb8aa3b, v122
	v_exp_f32_e32 v127, v127
	v_pk_mul_f32 v[140:141], v[134:135], v[140:141]
	v_mul_f32_e32 v134, 0xbfb8aa3b, v137
	v_exp_f32_e32 v134, v134
	v_mul_f32_e32 v123, 0xbfb8aa3b, v123
	v_exp_f32_e32 v122, v122
	v_exp_f32_e32 v123, v123
	v_add_f32_e32 v134, 1.0, v134
	v_rcp_f32_e32 v137, v134
	v_pk_add_f32 v[126:127], v[126:127], 1.0 op_sel_hi:[1,0]
	v_lshlrev_b32_e32 v134, 16, v177
	v_and_b32_e32 v135, 0xffff0000, v177
	v_rcp_f32_e32 v126, v126
	v_add_f32_e32 v122, 1.0, v122
	v_rcp_f32_e32 v127, v127
	v_add_f32_e32 v123, 1.0, v123
	v_pk_mul_f32 v[148:149], v[136:137], v[134:135]
	v_rcp_f32_e32 v122, v122
	v_rcp_f32_e32 v123, v123
	v_cvt_pk_bf16_f32 v134, v138, v139
	v_cvt_pk_bf16_f32 v135, v140, v141
	v_cvt_pk_bf16_f32 v136, v146, v147
	v_cvt_pk_bf16_f32 v137, v148, v149
	global_store_dwordx4 v[150:151], v[134:137], off offset:256
	v_mul_f32_e32 v114, 0xbfb8aa3b, v114
	v_mul_f32_e32 v115, 0xbfb8aa3b, v115
	s_waitcnt vmcnt(14)
	v_lshlrev_b32_e32 v134, 16, v166
	v_and_b32_e32 v135, 0xffff0000, v166
	v_pk_mul_f32 v[126:127], v[126:127], v[134:135]
	v_lshlrev_b32_e32 v134, 16, v168
	v_and_b32_e32 v135, 0xffff0000, v168
	v_pk_mul_f32 v[134:135], v[122:123], v[134:135]
	v_mul_f32_e32 v123, 0xbfb8aa3b, v124
	v_exp_f32_e32 v123, v123
	v_mul_f32_e32 v122, 0xbfb8aa3b, v128
	v_exp_f32_e32 v122, v122
	v_lshlrev_b32_e32 v128, 16, v167
	v_add_f32_e32 v123, 1.0, v123
	v_rcp_f32_e32 v124, v123
	v_mul_f32_e32 v123, 0xbfb8aa3b, v129
	v_exp_f32_e32 v123, v123
	v_add_f32_e32 v122, 1.0, v122
	v_rcp_f32_e32 v122, v122
	v_and_b32_e32 v129, 0xffff0000, v167
	v_add_f32_e32 v123, 1.0, v123
	v_rcp_f32_e32 v123, v123
	v_exp_f32_e32 v114, v114
	v_mul_f32_e32 v110, 0xbfb8aa3b, v110
	v_exp_f32_e32 v115, v115
	v_pk_mul_f32 v[128:129], v[122:123], v[128:129]
	v_mul_f32_e32 v122, 0xbfb8aa3b, v125
	v_exp_f32_e32 v122, v122
	v_mul_f32_e32 v111, 0xbfb8aa3b, v111
	v_exp_f32_e32 v110, v110
	v_exp_f32_e32 v111, v111
	v_add_f32_e32 v122, 1.0, v122
	v_rcp_f32_e32 v125, v122
	v_pk_add_f32 v[114:115], v[114:115], 1.0 op_sel_hi:[1,0]
	v_lshlrev_b32_e32 v122, 16, v169
	v_and_b32_e32 v123, 0xffff0000, v169
	v_rcp_f32_e32 v114, v114
	v_add_f32_e32 v110, 1.0, v110
	v_rcp_f32_e32 v115, v115
	v_add_f32_e32 v111, 1.0, v111
	v_pk_mul_f32 v[136:137], v[124:125], v[122:123]
	v_cvt_pk_bf16_f32 v122, v126, v127
	v_add_co_u32_e32 v126, vcc, s9, v212
	v_rcp_f32_e32 v110, v110
	v_rcp_f32_e32 v111, v111
	v_cvt_pk_bf16_f32 v123, v128, v129
	v_cvt_pk_bf16_f32 v124, v134, v135
	v_cvt_pk_bf16_f32 v125, v136, v137
	v_addc_co_u32_e32 v127, vcc, 0, v213, vcc
	global_store_dwordx4 v[126:127], v[122:125], off
	v_mul_f32_e32 v102, 0xbfb8aa3b, v102
	v_mul_f32_e32 v103, 0xbfb8aa3b, v103
	s_waitcnt vmcnt(14)
; __device__ __forceinline__ unsigned pk2(float lo, float hi) { const f32x2 v = {lo, hi}; const bf16x2_hw b = __builtin_convertvector(v, bf16x2_hw); return __builtin_bit_cast(unsigned, b); }
; __device__ __forceinline__ void unpack8(const u32x4 w, float (&v)[8]) { v[0] = bflo(w.x); v[1] = bfhi(w.x); v[2] = bflo(w.y); v[3] = bfhi(w.y); v[4] = bflo(w.z); v[5] = bfhi(w.z); v[6] = bflo(w.w); v[7] = bfhi(w.w); }
; __device__ __forceinline__ u32x4 pack8(const float (&v)[8]) { u32x4 w; w.x = pk2(v[0], v[1]); w.y = pk2(v[2], v[3]); w.z = pk2(v[4], v[5]); w.w = pk2(v[6], v[7]); return w; }
; __device__ __forceinline__ float sigmoidf_(float x) { return __builtin_amdgcn_rcpf(1.0f + __builtin_amdgcn_exp2f(-LOG2E * x)); }
;     __device__ __forceinline__ bool operator()(Acc& acc, const Unit& u, int wr, int wc, int fr, int fq, const LAS float*) const {
;     ...
; #pragma unroll
;         for (int ai = 0; ai < 2; ++ai) {
; #pragma unroll
;             for (int m = 0; m < 4; ++m)
; #pragma unroll
;                 for (int bj = 0; bj < 2; ++bj) {
;                     float y[8]; unpack8(yv[ai][m][bj], y);
;                     float v[8];
; #pragma unroll
;                     for (int e = 0; e < 4; ++e) { v[e] = y[e] * sigmoidf_(acc[ai][bj][m][0][e]); v[4 + e] = y[4 + e] * sigmoidf_(acc[ai][bj][m][1][e]); }
;                     gst<u32x4>(zp + (ai * HALF + m * 16) * 512 + bj * HALF, pack8(v));
;                 }
;             asm volatile("" ::: "memory");
;         }
	v_lshlrev_b32_e32 v122, 16, v154
	v_and_b32_e32 v123, 0xffff0000, v154
	v_pk_mul_f32 v[114:115], v[114:115], v[122:123]
	v_lshlrev_b32_e32 v122, 16, v156
	v_and_b32_e32 v123, 0xffff0000, v156
	v_pk_mul_f32 v[122:123], v[110:111], v[122:123]
	v_mul_f32_e32 v111, 0xbfb8aa3b, v112
	v_exp_f32_e32 v111, v111
	v_mul_f32_e32 v110, 0xbfb8aa3b, v116
	v_exp_f32_e32 v110, v110
	v_lshlrev_b32_e32 v116, 16, v155
	v_add_f32_e32 v111, 1.0, v111
	v_rcp_f32_e32 v112, v111
	v_mul_f32_e32 v111, 0xbfb8aa3b, v117
	v_exp_f32_e32 v111, v111
	v_add_f32_e32 v110, 1.0, v110
	v_rcp_f32_e32 v110, v110
	v_and_b32_e32 v117, 0xffff0000, v155
	v_add_f32_e32 v111, 1.0, v111
	v_rcp_f32_e32 v111, v111
	v_exp_f32_e32 v102, v102
	v_mul_f32_e32 v98, 0xbfb8aa3b, v98
	v_exp_f32_e32 v103, v103
	v_pk_mul_f32 v[116:117], v[110:111], v[116:117]
	v_mul_f32_e32 v110, 0xbfb8aa3b, v113
	v_exp_f32_e32 v110, v110
	v_mul_f32_e32 v99, 0xbfb8aa3b, v99
	v_exp_f32_e32 v98, v98
	v_exp_f32_e32 v99, v99
	v_add_f32_e32 v110, 1.0, v110
	v_rcp_f32_e32 v113, v110
	v_pk_add_f32 v[102:103], v[102:103], 1.0 op_sel_hi:[1,0]
	v_lshlrev_b32_e32 v110, 16, v157
	v_and_b32_e32 v111, 0xffff0000, v157
	v_rcp_f32_e32 v102, v102
	v_add_f32_e32 v98, 1.0, v98
	v_rcp_f32_e32 v103, v103
	v_add_f32_e32 v99, 1.0, v99
	v_pk_mul_f32 v[124:125], v[112:113], v[110:111]
	v_rcp_f32_e32 v98, v98
	v_rcp_f32_e32 v99, v99
	v_cvt_pk_bf16_f32 v110, v114, v115
	v_cvt_pk_bf16_f32 v111, v116, v117
	v_cvt_pk_bf16_f32 v112, v122, v123
	v_cvt_pk_bf16_f32 v113, v124, v125
	global_store_dwordx4 v[126:127], v[110:113], off offset:256
	v_mul_f32_e32 v90, 0xbfb8aa3b, v90
	v_mul_f32_e32 v91, 0xbfb8aa3b, v91
	s_waitcnt vmcnt(14)
	v_lshlrev_b32_e32 v110, 16, v142
	v_and_b32_e32 v111, 0xffff0000, v142
	v_pk_mul_f32 v[102:103], v[102:103], v[110:111]
	v_lshlrev_b32_e32 v110, 16, v144
	v_and_b32_e32 v111, 0xffff0000, v144
	v_pk_mul_f32 v[110:111], v[98:99], v[110:111]
	v_mul_f32_e32 v99, 0xbfb8aa3b, v100
	v_exp_f32_e32 v99, v99
	v_mul_f32_e32 v98, 0xbfb8aa3b, v104
	v_exp_f32_e32 v98, v98
	v_lshlrev_b32_e32 v104, 16, v143
	v_add_f32_e32 v99, 1.0, v99
	v_rcp_f32_e32 v100, v99
	v_mul_f32_e32 v99, 0xbfb8aa3b, v105
	v_exp_f32_e32 v99, v99
	v_add_f32_e32 v98, 1.0, v98
	v_rcp_f32_e32 v98, v98
	v_and_b32_e32 v105, 0xffff0000, v143
	v_add_f32_e32 v99, 1.0, v99
	v_rcp_f32_e32 v99, v99
	v_exp_f32_e32 v90, v90
	v_mul_f32_e32 v86, 0xbfb8aa3b, v86
	v_exp_f32_e32 v91, v91
	v_pk_mul_f32 v[104:105], v[98:99], v[104:105]
	v_mul_f32_e32 v98, 0xbfb8aa3b, v101
	v_exp_f32_e32 v98, v98
	v_mul_f32_e32 v87, 0xbfb8aa3b, v87
	v_exp_f32_e32 v86, v86
	v_exp_f32_e32 v87, v87
	v_add_f32_e32 v98, 1.0, v98
	v_rcp_f32_e32 v101, v98
	v_pk_add_f32 v[90:91], v[90:91], 1.0 op_sel_hi:[1,0]
	v_lshlrev_b32_e32 v98, 16, v145
	v_and_b32_e32 v99, 0xffff0000, v145
	v_rcp_f32_e32 v90, v90
	v_add_f32_e32 v86, 1.0, v86
	v_rcp_f32_e32 v91, v91
	v_add_f32_e32 v87, 1.0, v87
	v_pk_mul_f32 v[112:113], v[100:101], v[98:99]
	v_cvt_pk_bf16_f32 v98, v102, v103
	v_add_co_u32_e32 v102, vcc, s10, v212
	v_rcp_f32_e32 v86, v86
	v_rcp_f32_e32 v87, v87
	v_cvt_pk_bf16_f32 v99, v104, v105
	v_cvt_pk_bf16_f32 v100, v110, v111
	v_cvt_pk_bf16_f32 v101, v112, v113
	v_addc_co_u32_e32 v103, vcc, 0, v213, vcc
	global_store_dwordx4 v[102:103], v[98:101], off
	v_mul_f32_e32 v78, 0xbfb8aa3b, v78
	v_mul_f32_e32 v79, 0xbfb8aa3b, v79
	s_waitcnt vmcnt(14)
	v_lshlrev_b32_e32 v98, 16, v130
	v_and_b32_e32 v99, 0xffff0000, v130
	v_pk_mul_f32 v[90:91], v[90:91], v[98:99]
	v_lshlrev_b32_e32 v98, 16, v132
	v_and_b32_e32 v99, 0xffff0000, v132
	v_pk_mul_f32 v[98:99], v[86:87], v[98:99]
	v_mul_f32_e32 v87, 0xbfb8aa3b, v88
	v_exp_f32_e32 v87, v87
	v_mul_f32_e32 v86, 0xbfb8aa3b, v92
	v_exp_f32_e32 v86, v86
	v_lshlrev_b32_e32 v92, 16, v131
	v_add_f32_e32 v87, 1.0, v87
	v_rcp_f32_e32 v88, v87
	v_mul_f32_e32 v87, 0xbfb8aa3b, v93
	v_exp_f32_e32 v87, v87
	v_add_f32_e32 v86, 1.0, v86
	v_rcp_f32_e32 v86, v86
	v_and_b32_e32 v93, 0xffff0000, v131
	v_add_f32_e32 v87, 1.0, v87
	v_rcp_f32_e32 v87, v87
	v_exp_f32_e32 v78, v78
	v_mul_f32_e32 v74, 0xbfb8aa3b, v74
	v_exp_f32_e32 v79, v79
	v_pk_mul_f32 v[92:93], v[86:87], v[92:93]
	v_mul_f32_e32 v86, 0xbfb8aa3b, v89
	v_exp_f32_e32 v86, v86
	v_mul_f32_e32 v75, 0xbfb8aa3b, v75
	v_exp_f32_e32 v74, v74
	v_exp_f32_e32 v75, v75
	v_add_f32_e32 v86, 1.0, v86
	v_rcp_f32_e32 v89, v86
	v_pk_add_f32 v[78:79], v[78:79], 1.0 op_sel_hi:[1,0]
	v_lshlrev_b32_e32 v86, 16, v133
	v_and_b32_e32 v87, 0xffff0000, v133
	v_rcp_f32_e32 v78, v78
	v_add_f32_e32 v74, 1.0, v74
	v_rcp_f32_e32 v79, v79
	v_add_f32_e32 v75, 1.0, v75
	v_pk_mul_f32 v[100:101], v[88:89], v[86:87]
	v_rcp_f32_e32 v74, v74
	v_rcp_f32_e32 v75, v75
	v_cvt_pk_bf16_f32 v86, v90, v91
	v_cvt_pk_bf16_f32 v87, v92, v93
	v_cvt_pk_bf16_f32 v88, v98, v99
	v_cvt_pk_bf16_f32 v89, v100, v101
	global_store_dwordx4 v[102:103], v[86:89], off offset:256
	v_mul_f32_e32 v66, 0xbfb8aa3b, v66
	v_mul_f32_e32 v67, 0xbfb8aa3b, v67
	s_waitcnt vmcnt(14)
; __device__ __forceinline__ unsigned pk2(float lo, float hi) { const f32x2 v = {lo, hi}; const bf16x2_hw b = __builtin_convertvector(v, bf16x2_hw); return __builtin_bit_cast(unsigned, b); }
; __device__ __forceinline__ void unpack8(const u32x4 w, float (&v)[8]) { v[0] = bflo(w.x); v[1] = bfhi(w.x); v[2] = bflo(w.y); v[3] = bfhi(w.y); v[4] = bflo(w.z); v[5] = bfhi(w.z); v[6] = bflo(w.w); v[7] = bfhi(w.w); }
; __device__ __forceinline__ u32x4 pack8(const float (&v)[8]) { u32x4 w; w.x = pk2(v[0], v[1]); w.y = pk2(v[2], v[3]); w.z = pk2(v[4], v[5]); w.w = pk2(v[6], v[7]); return w; }
; __device__ __forceinline__ float sigmoidf_(float x) { return __builtin_amdgcn_rcpf(1.0f + __builtin_amdgcn_exp2f(-LOG2E * x)); }
;     __device__ __forceinline__ bool operator()(Acc& acc, const Unit& u, int wr, int wc, int fr, int fq, const LAS float*) const {
;     ...
; #pragma unroll
;         for (int ai = 0; ai < 2; ++ai) {
; #pragma unroll
;             for (int m = 0; m < 4; ++m)
; #pragma unroll
;                 for (int bj = 0; bj < 2; ++bj) {
;                     float y[8]; unpack8(yv[ai][m][bj], y);
;                     float v[8];
; #pragma unroll
;                     for (int e = 0; e < 4; ++e) { v[e] = y[e] * sigmoidf_(acc[ai][bj][m][0][e]); v[4 + e] = y[4 + e] * sigmoidf_(acc[ai][bj][m][1][e]); }
;                     gst<u32x4>(zp + (ai * HALF + m * 16) * 512 + bj * HALF, pack8(v));
;                 }
;             asm volatile("" ::: "memory");
;         }
	v_lshlrev_b32_e32 v86, 16, v118
	v_and_b32_e32 v87, 0xffff0000, v118
	v_pk_mul_f32 v[78:79], v[78:79], v[86:87]
	v_lshlrev_b32_e32 v86, 16, v120
	v_and_b32_e32 v87, 0xffff0000, v120
	v_pk_mul_f32 v[86:87], v[74:75], v[86:87]
	v_mul_f32_e32 v75, 0xbfb8aa3b, v76
	v_exp_f32_e32 v75, v75
	v_mul_f32_e32 v74, 0xbfb8aa3b, v80
	v_exp_f32_e32 v74, v74
	v_lshlrev_b32_e32 v80, 16, v119
	v_add_f32_e32 v75, 1.0, v75
	v_rcp_f32_e32 v76, v75
	v_mul_f32_e32 v75, 0xbfb8aa3b, v81
	v_exp_f32_e32 v75, v75
	v_add_f32_e32 v74, 1.0, v74
	v_rcp_f32_e32 v74, v74
	v_and_b32_e32 v81, 0xffff0000, v119
	v_add_f32_e32 v75, 1.0, v75
	v_rcp_f32_e32 v75, v75
	v_exp_f32_e32 v66, v66
	v_mul_f32_e32 v62, 0xbfb8aa3b, v62
	v_exp_f32_e32 v67, v67
	v_pk_mul_f32 v[80:81], v[74:75], v[80:81]
	v_mul_f32_e32 v74, 0xbfb8aa3b, v77
	v_exp_f32_e32 v74, v74
	v_mul_f32_e32 v63, 0xbfb8aa3b, v63
	v_exp_f32_e32 v62, v62
	v_exp_f32_e32 v63, v63
	v_add_f32_e32 v74, 1.0, v74
	v_rcp_f32_e32 v77, v74
	v_pk_add_f32 v[66:67], v[66:67], 1.0 op_sel_hi:[1,0]
	v_lshlrev_b32_e32 v74, 16, v121
	v_and_b32_e32 v75, 0xffff0000, v121
	v_rcp_f32_e32 v66, v66
	v_add_f32_e32 v62, 1.0, v62
	v_rcp_f32_e32 v67, v67
	v_add_f32_e32 v63, 1.0, v63
	v_pk_mul_f32 v[88:89], v[76:77], v[74:75]
	v_cvt_pk_bf16_f32 v74, v78, v79
	v_add_co_u32_e32 v78, vcc, s79, v212
	v_rcp_f32_e32 v62, v62
	v_rcp_f32_e32 v63, v63
	global_store_dwordx4 v[212:213], v[178:181], off
	v_cvt_pk_bf16_f32 v75, v80, v81
	v_cvt_pk_bf16_f32 v76, v86, v87
	v_cvt_pk_bf16_f32 v77, v88, v89
	v_addc_co_u32_e32 v79, vcc, 0, v213, vcc
	global_store_dwordx4 v[78:79], v[74:77], off
	v_mul_f32_e32 v54, 0xbfb8aa3b, v54
	v_mul_f32_e32 v55, 0xbfb8aa3b, v55
	s_waitcnt vmcnt(15)
	v_lshlrev_b32_e32 v74, 16, v106
	v_and_b32_e32 v75, 0xffff0000, v106
	v_pk_mul_f32 v[66:67], v[66:67], v[74:75]
	v_lshlrev_b32_e32 v74, 16, v108
	v_and_b32_e32 v75, 0xffff0000, v108
	v_pk_mul_f32 v[74:75], v[62:63], v[74:75]
	v_mul_f32_e32 v63, 0xbfb8aa3b, v64
	v_exp_f32_e32 v63, v63
	v_mul_f32_e32 v62, 0xbfb8aa3b, v68
	v_exp_f32_e32 v62, v62
	v_lshlrev_b32_e32 v68, 16, v107
	v_add_f32_e32 v63, 1.0, v63
	v_rcp_f32_e32 v64, v63
	v_mul_f32_e32 v63, 0xbfb8aa3b, v69
	v_exp_f32_e32 v63, v63
	v_add_f32_e32 v62, 1.0, v62
	v_rcp_f32_e32 v62, v62
	v_and_b32_e32 v69, 0xffff0000, v107
	v_add_f32_e32 v63, 1.0, v63
	v_rcp_f32_e32 v63, v63
	v_exp_f32_e32 v54, v54
	v_mul_f32_e32 v50, 0xbfb8aa3b, v50
	v_exp_f32_e32 v55, v55
	v_pk_mul_f32 v[68:69], v[62:63], v[68:69]
	v_mul_f32_e32 v62, 0xbfb8aa3b, v65
	v_exp_f32_e32 v62, v62
	v_mul_f32_e32 v51, 0xbfb8aa3b, v51
	v_exp_f32_e32 v50, v50
	v_exp_f32_e32 v51, v51
	v_add_f32_e32 v62, 1.0, v62
	v_rcp_f32_e32 v65, v62
	v_pk_add_f32 v[54:55], v[54:55], 1.0 op_sel_hi:[1,0]
	v_lshlrev_b32_e32 v62, 16, v109
	v_and_b32_e32 v63, 0xffff0000, v109
	v_rcp_f32_e32 v54, v54
	v_add_f32_e32 v50, 1.0, v50
	v_rcp_f32_e32 v55, v55
	v_add_f32_e32 v51, 1.0, v51
	v_pk_mul_f32 v[76:77], v[64:65], v[62:63]
	v_rcp_f32_e32 v50, v50
	v_rcp_f32_e32 v51, v51
	v_cvt_pk_bf16_f32 v62, v66, v67
	v_cvt_pk_bf16_f32 v63, v68, v69
	v_cvt_pk_bf16_f32 v64, v74, v75
	v_cvt_pk_bf16_f32 v65, v76, v77
	global_store_dwordx4 v[78:79], v[62:65], off offset:256
	v_mul_f32_e32 v42, 0xbfb8aa3b, v42
	v_mul_f32_e32 v43, 0xbfb8aa3b, v43
	s_waitcnt vmcnt(15)
	v_lshlrev_b32_e32 v62, 16, v94
	v_and_b32_e32 v63, 0xffff0000, v94
	v_pk_mul_f32 v[54:55], v[54:55], v[62:63]
	v_lshlrev_b32_e32 v62, 16, v96
	v_and_b32_e32 v63, 0xffff0000, v96
	v_pk_mul_f32 v[62:63], v[50:51], v[62:63]
	v_mul_f32_e32 v51, 0xbfb8aa3b, v52
	v_exp_f32_e32 v51, v51
	v_mul_f32_e32 v50, 0xbfb8aa3b, v56
	v_exp_f32_e32 v50, v50
	v_lshlrev_b32_e32 v56, 16, v95
	v_add_f32_e32 v51, 1.0, v51
	v_rcp_f32_e32 v52, v51
	v_mul_f32_e32 v51, 0xbfb8aa3b, v57
	v_exp_f32_e32 v51, v51
	v_add_f32_e32 v50, 1.0, v50
	v_rcp_f32_e32 v50, v50
	v_and_b32_e32 v57, 0xffff0000, v95
	v_add_f32_e32 v51, 1.0, v51
	v_rcp_f32_e32 v51, v51
	v_exp_f32_e32 v42, v42
	v_mul_f32_e32 v38, 0xbfb8aa3b, v38
	v_exp_f32_e32 v43, v43
	v_pk_mul_f32 v[56:57], v[50:51], v[56:57]
	v_mul_f32_e32 v50, 0xbfb8aa3b, v53
	v_exp_f32_e32 v50, v50
	v_mul_f32_e32 v39, 0xbfb8aa3b, v39
	v_exp_f32_e32 v38, v38
	v_exp_f32_e32 v39, v39
	v_add_f32_e32 v50, 1.0, v50
	v_rcp_f32_e32 v53, v50
	v_pk_add_f32 v[42:43], v[42:43], 1.0 op_sel_hi:[1,0]
	v_lshlrev_b32_e32 v50, 16, v97
	v_and_b32_e32 v51, 0xffff0000, v97
	v_rcp_f32_e32 v42, v42
	v_add_f32_e32 v38, 1.0, v38
	v_rcp_f32_e32 v43, v43
	v_add_f32_e32 v39, 1.0, v39
	v_pk_mul_f32 v[64:65], v[52:53], v[50:51]
	v_cvt_pk_bf16_f32 v50, v54, v55
	v_add_co_u32_e32 v54, vcc, s11, v212
	v_rcp_f32_e32 v38, v38
	v_rcp_f32_e32 v39, v39
	v_cvt_pk_bf16_f32 v51, v56, v57
	v_cvt_pk_bf16_f32 v52, v62, v63
	v_cvt_pk_bf16_f32 v53, v64, v65
	v_addc_co_u32_e32 v55, vcc, 0, v213, vcc
	global_store_dwordx4 v[54:55], v[50:53], off
	v_mul_f32_e32 v30, 0xbfb8aa3b, v30
	v_mul_f32_e32 v31, 0xbfb8aa3b, v31
	s_waitcnt vmcnt(15)
; __device__ __forceinline__ unsigned pk2(float lo, float hi) { const f32x2 v = {lo, hi}; const bf16x2_hw b = __builtin_convertvector(v, bf16x2_hw); return __builtin_bit_cast(unsigned, b); }
; __device__ __forceinline__ void unpack8(const u32x4 w, float (&v)[8]) { v[0] = bflo(w.x); v[1] = bfhi(w.x); v[2] = bflo(w.y); v[3] = bfhi(w.y); v[4] = bflo(w.z); v[5] = bfhi(w.z); v[6] = bflo(w.w); v[7] = bfhi(w.w); }
; __device__ __forceinline__ u32x4 pack8(const float (&v)[8]) { u32x4 w; w.x = pk2(v[0], v[1]); w.y = pk2(v[2], v[3]); w.z = pk2(v[4], v[5]); w.w = pk2(v[6], v[7]); return w; }
; __device__ __forceinline__ float sigmoidf_(float x) { return __builtin_amdgcn_rcpf(1.0f + __builtin_amdgcn_exp2f(-LOG2E * x)); }
;     __device__ __forceinline__ bool operator()(Acc& acc, const Unit& u, int wr, int wc, int fr, int fq, const LAS float*) const {
;     ...
; #pragma unroll
;         for (int ai = 0; ai < 2; ++ai) {
; #pragma unroll
;             for (int m = 0; m < 4; ++m)
; #pragma unroll
;                 for (int bj = 0; bj < 2; ++bj) {
;                     float y[8]; unpack8(yv[ai][m][bj], y);
;                     float v[8];
; #pragma unroll
;                     for (int e = 0; e < 4; ++e) { v[e] = y[e] * sigmoidf_(acc[ai][bj][m][0][e]); v[4 + e] = y[4 + e] * sigmoidf_(acc[ai][bj][m][1][e]); }
;                     gst<u32x4>(zp + (ai * HALF + m * 16) * 512 + bj * HALF, pack8(v));
;                 }
;             asm volatile("" ::: "memory");
;         }
	v_lshlrev_b32_e32 v50, 16, v82
	v_and_b32_e32 v51, 0xffff0000, v82
	v_pk_mul_f32 v[42:43], v[42:43], v[50:51]
	v_lshlrev_b32_e32 v50, 16, v84
	v_and_b32_e32 v51, 0xffff0000, v84
	v_pk_mul_f32 v[50:51], v[38:39], v[50:51]
	v_mul_f32_e32 v39, 0xbfb8aa3b, v40
	v_exp_f32_e32 v39, v39
	v_mul_f32_e32 v38, 0xbfb8aa3b, v44
	v_exp_f32_e32 v38, v38
	v_lshlrev_b32_e32 v44, 16, v83
	v_add_f32_e32 v39, 1.0, v39
	v_rcp_f32_e32 v40, v39
	v_mul_f32_e32 v39, 0xbfb8aa3b, v45
	v_exp_f32_e32 v39, v39
	v_add_f32_e32 v38, 1.0, v38
	v_rcp_f32_e32 v38, v38
	v_and_b32_e32 v45, 0xffff0000, v83
	v_add_f32_e32 v39, 1.0, v39
	v_rcp_f32_e32 v39, v39
	v_exp_f32_e32 v30, v30
	v_mul_f32_e32 v26, 0xbfb8aa3b, v26
	v_exp_f32_e32 v31, v31
	v_pk_mul_f32 v[44:45], v[38:39], v[44:45]
	v_mul_f32_e32 v38, 0xbfb8aa3b, v41
	v_exp_f32_e32 v38, v38
	v_mul_f32_e32 v27, 0xbfb8aa3b, v27
	v_exp_f32_e32 v26, v26
	v_exp_f32_e32 v27, v27
	v_add_f32_e32 v38, 1.0, v38
	v_rcp_f32_e32 v41, v38
	v_pk_add_f32 v[30:31], v[30:31], 1.0 op_sel_hi:[1,0]
	v_lshlrev_b32_e32 v38, 16, v85
	v_and_b32_e32 v39, 0xffff0000, v85
	v_rcp_f32_e32 v30, v30
	v_add_f32_e32 v26, 1.0, v26
	v_rcp_f32_e32 v31, v31
	v_add_f32_e32 v27, 1.0, v27
	v_pk_mul_f32 v[52:53], v[40:41], v[38:39]
	v_rcp_f32_e32 v26, v26
	v_rcp_f32_e32 v27, v27
	v_cvt_pk_bf16_f32 v38, v42, v43
	v_cvt_pk_bf16_f32 v39, v44, v45
	v_cvt_pk_bf16_f32 v40, v50, v51
	v_cvt_pk_bf16_f32 v41, v52, v53
	global_store_dwordx4 v[54:55], v[38:41], off offset:256
	v_mul_f32_e32 v22, 0xbfb8aa3b, v22
	v_mul_f32_e32 v23, 0xbfb8aa3b, v23
	s_waitcnt vmcnt(15)
	v_lshlrev_b32_e32 v38, 16, v70
	v_and_b32_e32 v39, 0xffff0000, v70
	v_pk_mul_f32 v[30:31], v[30:31], v[38:39]
	v_lshlrev_b32_e32 v38, 16, v72
	v_and_b32_e32 v39, 0xffff0000, v72
	v_pk_mul_f32 v[38:39], v[26:27], v[38:39]
	v_mul_f32_e32 v27, 0xbfb8aa3b, v28
	v_exp_f32_e32 v27, v27
	v_mul_f32_e32 v26, 0xbfb8aa3b, v32
	v_exp_f32_e32 v26, v26
	v_lshlrev_b32_e32 v32, 16, v71
	v_add_f32_e32 v27, 1.0, v27
	v_rcp_f32_e32 v28, v27
	v_mul_f32_e32 v27, 0xbfb8aa3b, v33
	v_exp_f32_e32 v27, v27
	v_add_f32_e32 v26, 1.0, v26
	v_rcp_f32_e32 v26, v26
	v_and_b32_e32 v33, 0xffff0000, v71
	v_add_f32_e32 v27, 1.0, v27
	v_rcp_f32_e32 v27, v27
	v_exp_f32_e32 v22, v22
	v_mul_f32_e32 v18, 0xbfb8aa3b, v18
	v_exp_f32_e32 v23, v23
	v_pk_mul_f32 v[32:33], v[26:27], v[32:33]
	v_mul_f32_e32 v26, 0xbfb8aa3b, v29
	v_exp_f32_e32 v26, v26
	v_mul_f32_e32 v19, 0xbfb8aa3b, v19
	v_exp_f32_e32 v18, v18
	v_exp_f32_e32 v19, v19
	v_add_f32_e32 v26, 1.0, v26
	v_rcp_f32_e32 v29, v26
	v_pk_add_f32 v[22:23], v[22:23], 1.0 op_sel_hi:[1,0]
	v_lshlrev_b32_e32 v26, 16, v73
	v_and_b32_e32 v27, 0xffff0000, v73
	v_rcp_f32_e32 v22, v22
	v_add_f32_e32 v18, 1.0, v18
	v_rcp_f32_e32 v23, v23
	v_add_f32_e32 v19, 1.0, v19
	v_pk_mul_f32 v[40:41], v[28:29], v[26:27]
	v_cvt_pk_bf16_f32 v26, v30, v31
	v_add_co_u32_e32 v30, vcc, s12, v212
	v_rcp_f32_e32 v18, v18
	v_rcp_f32_e32 v19, v19
	v_cvt_pk_bf16_f32 v27, v32, v33
	v_cvt_pk_bf16_f32 v28, v38, v39
	v_cvt_pk_bf16_f32 v29, v40, v41
	v_addc_co_u32_e32 v31, vcc, 0, v213, vcc
	global_store_dwordx4 v[30:31], v[26:29], off
	v_mul_f32_e32 v14, 0xbfb8aa3b, v14
	v_mul_f32_e32 v15, 0xbfb8aa3b, v15
	s_waitcnt vmcnt(15)
; __device__ __forceinline__ void unpack8(const u32x4 w, float (&v)[8]) { v[0] = bflo(w.x); v[1] = bfhi(w.x); v[2] = bflo(w.y); v[3] = bfhi(w.y); v[4] = bflo(w.z); v[5] = bfhi(w.z); v[6] = bflo(w.w); v[7] = bfhi(w.w); }
; __device__ __forceinline__ u32x4 pack8(const float (&v)[8]) { u32x4 w; w.x = pk2(v[0], v[1]); w.y = pk2(v[2], v[3]); w.z = pk2(v[4], v[5]); w.w = pk2(v[6], v[7]); return w; }
; __device__ __forceinline__ float sigmoidf_(float x) { return __builtin_amdgcn_rcpf(1.0f + __builtin_amdgcn_exp2f(-LOG2E * x)); }
;     __device__ __forceinline__ bool operator()(Acc& acc, const Unit& u, int wr, int wc, int fr, int fq, const LAS float*) const {
;     ...
; #pragma unroll
;         for (int ai = 0; ai < 2; ++ai) {
; #pragma unroll
;             for (int m = 0; m < 4; ++m)
; #pragma unroll
;                 for (int bj = 0; bj < 2; ++bj) {
;                     float y[8]; unpack8(yv[ai][m][bj], y);
;                     float v[8];
; #pragma unroll
;                     for (int e = 0; e < 4; ++e) { v[e] = y[e] * sigmoidf_(acc[ai][bj][m][0][e]); v[4 + e] = y[4 + e] * sigmoidf_(acc[ai][bj][m][1][e]); }
;                     gst<u32x4>(zp + (ai * HALF + m * 16) * 512 + bj * HALF, pack8(v));
;                 }
;             asm volatile("" ::: "memory");
;         }
;         return true;
; template <class Epi, bool ALIGN_EPI, bool SP2, class Hook>
; __device__ __forceinline__ void gemm_phase(LAS unsigned char* lds, const Gemm g, const StaticOrder& S, const Epi& E, Acc& acc, const bool fresh, const Hook& H, const int wave_id) {
;     ...
;         if (!has_next) break;
;         if (reset) {
; #pragma unroll
;             for (int a = 0; a < 2; ++a)
; #pragma unroll
;                 for (int b = 0; b < 2; ++b)
; #pragma unroll
;                     for (int m = 0; m < 4; ++m)
; #pragma unroll
;                         for (int n = 0; n < 2; ++n) acc[a][b][m][n] = (f32x4){0.f, 0.f, 0.f, 0.f};
;         }
;         cur = nxt; cA = nA; cB = nB; ++ui;
	v_lshlrev_b32_e32 v26, 16, v58
	v_and_b32_e32 v27, 0xffff0000, v58
	v_pk_mul_f32 v[22:23], v[22:23], v[26:27]
	v_lshlrev_b32_e32 v26, 16, v60
	v_and_b32_e32 v27, 0xffff0000, v60
	v_pk_mul_f32 v[26:27], v[18:19], v[26:27]
	v_mul_f32_e32 v19, 0xbfb8aa3b, v20
	v_exp_f32_e32 v19, v19
	v_mul_f32_e32 v18, 0xbfb8aa3b, v24
	v_exp_f32_e32 v18, v18
	v_lshlrev_b32_e32 v24, 16, v59
	v_add_f32_e32 v19, 1.0, v19
	v_rcp_f32_e32 v20, v19
	v_mul_f32_e32 v19, 0xbfb8aa3b, v25
	v_exp_f32_e32 v19, v19
	v_add_f32_e32 v18, 1.0, v18
	v_rcp_f32_e32 v18, v18
	v_and_b32_e32 v25, 0xffff0000, v59
	v_add_f32_e32 v19, 1.0, v19
	v_rcp_f32_e32 v19, v19
	v_exp_f32_e32 v14, v14
	v_mul_f32_e32 v10, 0xbfb8aa3b, v10
	v_exp_f32_e32 v15, v15
	v_pk_mul_f32 v[24:25], v[18:19], v[24:25]
	v_mul_f32_e32 v18, 0xbfb8aa3b, v21
	v_exp_f32_e32 v18, v18
	v_mul_f32_e32 v11, 0xbfb8aa3b, v11
	v_exp_f32_e32 v10, v10
	v_exp_f32_e32 v11, v11
	v_add_f32_e32 v18, 1.0, v18
	v_rcp_f32_e32 v21, v18
	v_pk_add_f32 v[14:15], v[14:15], 1.0 op_sel_hi:[1,0]
	v_lshlrev_b32_e32 v18, 16, v61
	v_and_b32_e32 v19, 0xffff0000, v61
	v_rcp_f32_e32 v14, v14
	v_add_f32_e32 v10, 1.0, v10
	v_rcp_f32_e32 v15, v15
	v_add_f32_e32 v11, 1.0, v11
	v_pk_mul_f32 v[28:29], v[20:21], v[18:19]
	v_rcp_f32_e32 v10, v10
	v_rcp_f32_e32 v11, v11
	v_cvt_pk_bf16_f32 v18, v22, v23
	v_cvt_pk_bf16_f32 v19, v24, v25
	v_cvt_pk_bf16_f32 v20, v26, v27
	v_cvt_pk_bf16_f32 v21, v28, v29
	global_store_dwordx4 v[30:31], v[18:21], off offset:256
	v_mul_f32_e32 v6, 0xbfb8aa3b, v6
	v_mul_f32_e32 v7, 0xbfb8aa3b, v7
	s_waitcnt vmcnt(15)
	v_lshlrev_b32_e32 v18, 16, v46
	v_and_b32_e32 v19, 0xffff0000, v46
	v_pk_mul_f32 v[14:15], v[14:15], v[18:19]
	v_lshlrev_b32_e32 v18, 16, v48
	v_and_b32_e32 v19, 0xffff0000, v48
	v_pk_mul_f32 v[18:19], v[10:11], v[18:19]
	v_mul_f32_e32 v11, 0xbfb8aa3b, v12
	v_exp_f32_e32 v11, v11
	v_mul_f32_e32 v10, 0xbfb8aa3b, v16
	v_exp_f32_e32 v10, v10
	v_lshlrev_b32_e32 v16, 16, v47
	v_add_f32_e32 v11, 1.0, v11
	v_rcp_f32_e32 v12, v11
	v_mul_f32_e32 v11, 0xbfb8aa3b, v17
	v_exp_f32_e32 v11, v11
	v_add_f32_e32 v10, 1.0, v10
	v_rcp_f32_e32 v10, v10
	v_and_b32_e32 v17, 0xffff0000, v47
	v_add_f32_e32 v11, 1.0, v11
	v_rcp_f32_e32 v11, v11
	v_exp_f32_e32 v6, v6
	v_mul_f32_e32 v2, 0xbfb8aa3b, v2
	v_exp_f32_e32 v7, v7
	v_pk_mul_f32 v[16:17], v[10:11], v[16:17]
	v_mul_f32_e32 v10, 0xbfb8aa3b, v13
	v_exp_f32_e32 v10, v10
	v_mul_f32_e32 v3, 0xbfb8aa3b, v3
	v_exp_f32_e32 v2, v2
	v_exp_f32_e32 v3, v3
	v_add_f32_e32 v10, 1.0, v10
	v_rcp_f32_e32 v13, v10
	v_pk_add_f32 v[6:7], v[6:7], 1.0 op_sel_hi:[1,0]
	v_lshlrev_b32_e32 v10, 16, v49
	v_and_b32_e32 v11, 0xffff0000, v49
	v_rcp_f32_e32 v6, v6
	v_add_f32_e32 v2, 1.0, v2
	v_rcp_f32_e32 v7, v7
	v_add_f32_e32 v3, 1.0, v3
	v_pk_mul_f32 v[20:21], v[12:13], v[10:11]
	v_cvt_pk_bf16_f32 v10, v14, v15
	v_add_co_u32_e32 v14, vcc, s13, v212
	v_rcp_f32_e32 v2, v2
	v_rcp_f32_e32 v3, v3
	v_cvt_pk_bf16_f32 v11, v16, v17
	v_cvt_pk_bf16_f32 v12, v18, v19
	v_cvt_pk_bf16_f32 v13, v20, v21
	v_addc_co_u32_e32 v15, vcc, 0, v213, vcc
	global_store_dwordx4 v[14:15], v[10:13], off
	s_mov_b64 s[8:9], -1
	s_and_b64 vcc, exec, s[4:5]
	s_waitcnt vmcnt(15)
	v_lshlrev_b32_e32 v10, 16, v34
	v_and_b32_e32 v11, 0xffff0000, v34
	v_pk_mul_f32 v[6:7], v[6:7], v[10:11]
	v_lshlrev_b32_e32 v10, 16, v36
	v_and_b32_e32 v11, 0xffff0000, v36
	v_pk_mul_f32 v[10:11], v[2:3], v[10:11]
	v_mul_f32_e32 v3, 0xbfb8aa3b, v4
	v_exp_f32_e32 v3, v3
	v_mul_f32_e32 v2, 0xbfb8aa3b, v8
	v_exp_f32_e32 v2, v2
	v_lshlrev_b32_e32 v8, 16, v35
	v_add_f32_e32 v3, 1.0, v3
	v_rcp_f32_e32 v4, v3
	v_mul_f32_e32 v3, 0xbfb8aa3b, v9
	v_exp_f32_e32 v3, v3
	v_add_f32_e32 v2, 1.0, v2
	v_rcp_f32_e32 v2, v2
	v_and_b32_e32 v9, 0xffff0000, v35
	v_add_f32_e32 v3, 1.0, v3
	v_rcp_f32_e32 v3, v3
	s_nop 0
	v_pk_mul_f32 v[8:9], v[2:3], v[8:9]
	v_mul_f32_e32 v2, 0xbfb8aa3b, v5
	v_exp_f32_e32 v2, v2
	v_and_b32_e32 v3, 0xffff0000, v37
	v_add_f32_e32 v2, 1.0, v2
	v_rcp_f32_e32 v5, v2
	v_lshlrev_b32_e32 v2, 16, v37
	v_pk_mul_f32 v[12:13], v[4:5], v[2:3]
	v_cvt_pk_bf16_f32 v2, v6, v7
	v_cvt_pk_bf16_f32 v3, v8, v9
	v_cvt_pk_bf16_f32 v4, v10, v11
	v_cvt_pk_bf16_f32 v5, v12, v13
	global_store_dwordx4 v[14:15], v[2:5], off offset:256
	s_cbranch_vccnz .LBB0_690
	s_and_b64 vcc, exec, s[0:1]
	s_cbranch_vccnz .LBB0_689
	s_barrier
	s_branch .LBB0_689

; #define LAS __attribute__((address_space(3)))
; __device__ __forceinline__ u32x4 pack8(const float (&v)[8]) { u32x4 w; w.x = pk2(v[0], v[1]); w.y = pk2(v[2], v[3]); w.z = pk2(v[4], v[5]); w.w = pk2(v[6], v[7]); return w; }
;     __device__ __forceinline__ bool operator()(Acc& acc, const Unit& u, int wr, int wc, int fr, int fq, const LAS float* rstab) const {
;         bf16_t* p0 = H + (size_t)(u.pm * BM + wr * 64 + fr) * HD_PITCH + u.pn * HALF + wc * 32 + 8 * fq;
;         const LAS float* rsp = rstab + wr * 64 + fr;
; #pragma unroll
;         for (int ai = 0; ai < 2; ++ai)
; #pragma unroll
;             for (int m = 0; m < 4; ++m) {
;                 const float rs = rsp[ai * HALF + m * 16], nrs = -LOG2E * rs, rs2 = rs * rs;
;                 float v[8];
; #pragma unroll
;                 for (int n = 0; n < 2; ++n)
; #pragma unroll
;                     for (int e = 0; e < 4; ++e) {
;                         const float g = acc[ai][0][m][n][e], up = acc[ai][1][m][n][e];
;                         v[4 * n + e] = (g * up * rs2) * __builtin_amdgcn_rcpf(1.0f + __builtin_amdgcn_exp2f(g * nrs));
;                     }
;                 gst<u32x4>(p0 + (ai * HALF + m * 16) * HD_PITCH, pack8(v));
;                 asm volatile("" ::: "memory");
;             }
;         return true;
;     }
.LBB0_1470:
	v_readlane_b32 s12, v250, 1
	v_and_b32_e32 v0, 15, v2
	s_add_i32 s12, s14, s12
	v_or_b32_e32 v3, s12, v0
	v_readlane_b32 s12, v254, 57
	v_readlane_b32 s13, v254, 58
	v_pk_mul_f32 v[130:131], v[126:127], v[130:131]
	v_pk_mul_f32 v[122:123], v[118:119], v[122:123]
	s_waitcnt lgkmcnt(0)
	v_mov_b64_e32 v[142:143], s[12:13]
	s_movk_i32 s12, 0x1800
	v_mad_i64_i32 v[142:143], s[12:13], v3, s12, v[142:143]
	s_lshl_b32 s12, s52, 7
	s_ashr_i32 s13, s12, 31
	v_lshl_add_u64 v[144:145], s[12:13], 1, v[142:143]
	v_readlane_b32 s12, v250, 11
	v_pk_mul_f32 v[114:115], v[110:111], v[114:115]
	v_pk_mul_f32 v[106:107], v[102:103], v[106:107]
	v_lshl_add_u32 v142, v0, 2, s12
	ds_read_b32 v143, v142
	v_readlane_b32 s12, v254, 33
	s_mov_b32 s14, s12
	v_lshl_add_u64 v[144:145], v[144:145], 0, s[14:15]
	v_and_b32_e32 v0, 48, v2
	s_waitcnt lgkmcnt(0)
	v_mul_f32_e32 v146, 0xbfb8aa3b, v143
	v_pk_mul_f32 v[126:127], v[126:127], v[146:147] op_sel_hi:[1,0]
	v_exp_f32_e32 v126, v126
	v_exp_f32_e32 v127, v127
	v_lshl_add_u64 v[2:3], v[144:145], 0, v[0:1]
	v_mul_f32_e32 v0, v124, v146
	v_exp_f32_e32 v144, v0
	v_mul_f32_e32 v0, v125, v146
	v_exp_f32_e32 v145, v0
	v_mul_f32_e32 v0, v143, v143
	v_pk_mul_f32 v[124:125], v[124:125], v[128:129]
	v_pk_add_f32 v[126:127], v[126:127], 1.0 op_sel_hi:[1,0]
	v_pk_mul_f32 v[128:129], v[130:131], v[0:1] op_sel_hi:[1,0]
	v_pk_mul_f32 v[130:131], v[116:117], v[146:147] op_sel_hi:[1,0]
	v_rcp_f32_e32 v126, v126
	v_rcp_f32_e32 v127, v127
	v_exp_f32_e32 v130, v130
	v_exp_f32_e32 v131, v131
	v_pk_mul_f32 v[118:119], v[118:119], v[146:147] op_sel_hi:[1,0]
	v_exp_f32_e32 v118, v118
	v_exp_f32_e32 v119, v119
	v_add_f32_e32 v143, 1.0, v144
	v_pk_mul_f32 v[126:127], v[128:129], v[126:127]
	v_pk_add_f32 v[128:129], v[130:131], 1.0 op_sel_hi:[1,0]
	v_rcp_f32_e32 v144, v143
	v_add_f32_e32 v143, 1.0, v145
	v_rcp_f32_e32 v128, v128
	v_rcp_f32_e32 v129, v129
	v_pk_add_f32 v[118:119], v[118:119], 1.0 op_sel_hi:[1,0]
	v_rcp_f32_e32 v145, v143
	v_rcp_f32_e32 v118, v118
	v_rcp_f32_e32 v119, v119
	v_pk_mul_f32 v[116:117], v[116:117], v[120:121]
	v_pk_mul_f32 v[124:125], v[124:125], v[0:1] op_sel_hi:[1,0]
	v_pk_mul_f32 v[116:117], v[116:117], v[0:1] op_sel_hi:[1,0]
	v_pk_mul_f32 v[124:125], v[124:125], v[144:145]
	v_pk_mul_f32 v[120:121], v[116:117], v[128:129]
	v_pk_mul_f32 v[116:117], v[122:123], v[0:1] op_sel_hi:[1,0]
	v_readlane_b32 s13, v254, 34
	v_pk_mul_f32 v[122:123], v[116:117], v[118:119]
	v_cvt_pk_bf16_f32 v116, v124, v125
	v_cvt_pk_bf16_f32 v117, v126, v127
	v_cvt_pk_bf16_f32 v118, v120, v121
	v_cvt_pk_bf16_f32 v119, v122, v123
	global_store_dwordx4 v[2:3], v[116:119], off
	ds_read_b32 v0, v142 offset:64
	v_writelane_b32 v254, s12, 33
	v_pk_mul_f32 v[98:99], v[94:95], v[98:99]
	v_pk_mul_f32 v[90:91], v[86:87], v[90:91]
	v_writelane_b32 v254, s13, 34
	s_waitcnt lgkmcnt(0)
	v_mul_f32_e32 v118, 0xbfb8aa3b, v0
	v_pk_mul_f32 v[110:111], v[110:111], v[118:119] op_sel_hi:[1,0]
	v_exp_f32_e32 v110, v110
	v_exp_f32_e32 v111, v111
	v_mul_f32_e32 v0, v0, v0
	v_pk_mul_f32 v[116:117], v[108:109], v[118:119] op_sel_hi:[1,0]
	v_pk_mul_f32 v[108:109], v[108:109], v[112:113]
	v_pk_add_f32 v[110:111], v[110:111], 1.0 op_sel_hi:[1,0]
	v_pk_mul_f32 v[112:113], v[114:115], v[0:1] op_sel_hi:[1,0]
	v_pk_mul_f32 v[114:115], v[100:101], v[118:119] op_sel_hi:[1,0]
	v_rcp_f32_e32 v110, v110
	v_rcp_f32_e32 v111, v111
	v_exp_f32_e32 v114, v114
	v_exp_f32_e32 v115, v115
	v_pk_mul_f32 v[102:103], v[102:103], v[118:119] op_sel_hi:[1,0]
	v_exp_f32_e32 v116, v116
	v_exp_f32_e32 v117, v117
	v_exp_f32_e32 v102, v102
	v_exp_f32_e32 v103, v103
	v_pk_mul_f32 v[110:111], v[112:113], v[110:111]
	v_pk_add_f32 v[112:113], v[114:115], 1.0 op_sel_hi:[1,0]
	v_pk_add_f32 v[116:117], v[116:117], 1.0 op_sel_hi:[1,0]
	v_rcp_f32_e32 v112, v112
	v_rcp_f32_e32 v113, v113
	v_pk_add_f32 v[102:103], v[102:103], 1.0 op_sel_hi:[1,0]
	v_rcp_f32_e32 v116, v116
	v_rcp_f32_e32 v117, v117
	v_rcp_f32_e32 v102, v102
	v_rcp_f32_e32 v103, v103
	v_pk_mul_f32 v[100:101], v[100:101], v[104:105]
	v_pk_mul_f32 v[108:109], v[108:109], v[0:1] op_sel_hi:[1,0]
	v_pk_mul_f32 v[100:101], v[100:101], v[0:1] op_sel_hi:[1,0]
	s_mov_b32 s12, 0x18000
	v_pk_mul_f32 v[104:105], v[100:101], v[112:113]
	v_pk_mul_f32 v[100:101], v[106:107], v[0:1] op_sel_hi:[1,0]
	v_pk_mul_f32 v[108:109], v[108:109], v[116:117]
	v_pk_mul_f32 v[106:107], v[100:101], v[102:103]
	v_cvt_pk_bf16_f32 v102, v104, v105
	v_add_co_u32_e32 v104, vcc, s12, v2
	v_cvt_pk_bf16_f32 v100, v108, v109
	v_cvt_pk_bf16_f32 v101, v110, v111
	v_cvt_pk_bf16_f32 v103, v106, v107
	v_addc_co_u32_e32 v105, vcc, 0, v3, vcc
	global_store_dwordx4 v[104:105], v[100:103], off
	ds_read_b32 v0, v142 offset:128
	s_mov_b32 s12, 0x30000
	v_pk_mul_f32 v[82:83], v[78:79], v[82:83]
	v_pk_mul_f32 v[70:71], v[66:67], v[70:71]
	v_pk_mul_f32 v[58:59], v[54:55], v[58:59]
	s_waitcnt lgkmcnt(0)
; __device__ __forceinline__ u32x4 pack8(const float (&v)[8]) { u32x4 w; w.x = pk2(v[0], v[1]); w.y = pk2(v[2], v[3]); w.z = pk2(v[4], v[5]); w.w = pk2(v[6], v[7]); return w; }
;     __device__ __forceinline__ bool operator()(Acc& acc, const Unit& u, int wr, int wc, int fr, int fq, const LAS float* rstab) const {
;     ...
; #pragma unroll
;         for (int ai = 0; ai < 2; ++ai)
; #pragma unroll
;             for (int m = 0; m < 4; ++m) {
;                 const float rs = rsp[ai * HALF + m * 16], nrs = -LOG2E * rs, rs2 = rs * rs;
;                 float v[8];
; #pragma unroll
;                 for (int n = 0; n < 2; ++n)
; #pragma unroll
;                     for (int e = 0; e < 4; ++e) {
;                         const float g = acc[ai][0][m][n][e], up = acc[ai][1][m][n][e];
;                         v[4 * n + e] = (g * up * rs2) * __builtin_amdgcn_rcpf(1.0f + __builtin_amdgcn_exp2f(g * nrs));
;                     }
;                 gst<u32x4>(p0 + (ai * HALF + m * 16) * HD_PITCH, pack8(v));
;                 asm volatile("" ::: "memory");
;             }
	v_mul_f32_e32 v102, 0xbfb8aa3b, v0
	v_pk_mul_f32 v[94:95], v[94:95], v[102:103] op_sel_hi:[1,0]
	v_exp_f32_e32 v94, v94
	v_exp_f32_e32 v95, v95
	v_mul_f32_e32 v0, v0, v0
	v_pk_mul_f32 v[100:101], v[92:93], v[102:103] op_sel_hi:[1,0]
	v_pk_mul_f32 v[92:93], v[92:93], v[96:97]
	v_pk_add_f32 v[94:95], v[94:95], 1.0 op_sel_hi:[1,0]
	v_pk_mul_f32 v[96:97], v[98:99], v[0:1] op_sel_hi:[1,0]
	v_pk_mul_f32 v[98:99], v[84:85], v[102:103] op_sel_hi:[1,0]
	v_rcp_f32_e32 v94, v94
	v_rcp_f32_e32 v95, v95
	v_exp_f32_e32 v98, v98
	v_exp_f32_e32 v99, v99
	v_pk_mul_f32 v[86:87], v[86:87], v[102:103] op_sel_hi:[1,0]
	v_exp_f32_e32 v100, v100
	v_exp_f32_e32 v101, v101
	v_exp_f32_e32 v86, v86
	v_exp_f32_e32 v87, v87
	v_pk_mul_f32 v[94:95], v[96:97], v[94:95]
	v_pk_add_f32 v[96:97], v[98:99], 1.0 op_sel_hi:[1,0]
	v_pk_add_f32 v[100:101], v[100:101], 1.0 op_sel_hi:[1,0]
	v_rcp_f32_e32 v96, v96
	v_rcp_f32_e32 v97, v97
	v_pk_add_f32 v[86:87], v[86:87], 1.0 op_sel_hi:[1,0]
	v_rcp_f32_e32 v100, v100
	v_rcp_f32_e32 v101, v101
	v_rcp_f32_e32 v86, v86
	v_rcp_f32_e32 v87, v87
	v_pk_mul_f32 v[84:85], v[84:85], v[88:89]
	v_pk_mul_f32 v[92:93], v[92:93], v[0:1] op_sel_hi:[1,0]
	v_pk_mul_f32 v[84:85], v[84:85], v[0:1] op_sel_hi:[1,0]
	v_pk_mul_f32 v[92:93], v[92:93], v[100:101]
	v_pk_mul_f32 v[88:89], v[84:85], v[96:97]
	v_pk_mul_f32 v[84:85], v[90:91], v[0:1] op_sel_hi:[1,0]
	v_pk_mul_f32 v[50:51], v[46:47], v[50:51]
	v_pk_mul_f32 v[90:91], v[84:85], v[86:87]
	v_cvt_pk_bf16_f32 v86, v88, v89
	v_add_co_u32_e32 v88, vcc, s12, v2
	v_cvt_pk_bf16_f32 v84, v92, v93
	v_cvt_pk_bf16_f32 v85, v94, v95
	v_cvt_pk_bf16_f32 v87, v90, v91
	v_addc_co_u32_e32 v89, vcc, 0, v3, vcc
	global_store_dwordx4 v[88:89], v[84:87], off
	ds_read_b32 v0, v142 offset:192
	s_mov_b32 s12, 0x48000
	v_pk_mul_f32 v[42:43], v[38:39], v[42:43]
	v_pk_mul_f32 v[34:35], v[30:31], v[34:35]
	v_pk_mul_f32 v[26:27], v[22:23], v[26:27]
	s_waitcnt lgkmcnt(0)
	v_mul_f32_e32 v86, 0xbfb8aa3b, v0
	v_pk_mul_f32 v[78:79], v[78:79], v[86:87] op_sel_hi:[1,0]
	v_exp_f32_e32 v78, v78
	v_exp_f32_e32 v79, v79
	v_mul_f32_e32 v0, v0, v0
	v_pk_mul_f32 v[84:85], v[76:77], v[86:87] op_sel_hi:[1,0]
	v_pk_mul_f32 v[76:77], v[76:77], v[80:81]
	v_pk_add_f32 v[78:79], v[78:79], 1.0 op_sel_hi:[1,0]
	v_pk_mul_f32 v[80:81], v[82:83], v[0:1] op_sel_hi:[1,0]
	v_pk_mul_f32 v[82:83], v[64:65], v[86:87] op_sel_hi:[1,0]
	v_rcp_f32_e32 v78, v78
	v_rcp_f32_e32 v79, v79
	v_exp_f32_e32 v82, v82
	v_exp_f32_e32 v83, v83
	v_pk_mul_f32 v[66:67], v[66:67], v[86:87] op_sel_hi:[1,0]
	v_exp_f32_e32 v84, v84
	v_exp_f32_e32 v85, v85
	v_exp_f32_e32 v66, v66
	v_exp_f32_e32 v67, v67
	v_pk_mul_f32 v[78:79], v[80:81], v[78:79]
	v_pk_add_f32 v[80:81], v[82:83], 1.0 op_sel_hi:[1,0]
	v_pk_add_f32 v[84:85], v[84:85], 1.0 op_sel_hi:[1,0]
	v_rcp_f32_e32 v80, v80
	v_rcp_f32_e32 v81, v81
	v_pk_add_f32 v[66:67], v[66:67], 1.0 op_sel_hi:[1,0]
	v_rcp_f32_e32 v84, v84
	v_rcp_f32_e32 v85, v85
	v_rcp_f32_e32 v66, v66
	v_rcp_f32_e32 v67, v67
	v_pk_mul_f32 v[64:65], v[64:65], v[68:69]
	v_pk_mul_f32 v[76:77], v[76:77], v[0:1] op_sel_hi:[1,0]
	v_pk_mul_f32 v[64:65], v[64:65], v[0:1] op_sel_hi:[1,0]
	v_pk_mul_f32 v[76:77], v[76:77], v[84:85]
	v_pk_mul_f32 v[68:69], v[64:65], v[80:81]
	v_pk_mul_f32 v[64:65], v[70:71], v[0:1] op_sel_hi:[1,0]
	v_pk_mul_f32 v[18:19], v[14:15], v[18:19]
	v_pk_mul_f32 v[70:71], v[64:65], v[66:67]
	v_cvt_pk_bf16_f32 v66, v68, v69
	v_add_co_u32_e32 v68, vcc, s12, v2
	v_cvt_pk_bf16_f32 v64, v76, v77
	v_cvt_pk_bf16_f32 v65, v78, v79
	v_cvt_pk_bf16_f32 v67, v70, v71
	v_addc_co_u32_e32 v69, vcc, 0, v3, vcc
	global_store_dwordx4 v[68:69], v[64:67], off
	ds_read_b32 v0, v142 offset:512
	s_mov_b32 s12, 0xc0000
	v_pk_mul_f32 v[66:67], v[62:63], v[74:75]
	v_pk_mul_f32 v[10:11], v[6:7], v[10:11]
	s_waitcnt lgkmcnt(0)
	v_mul_f32_e32 v68, 0xbfb8aa3b, v0
	v_pk_mul_f32 v[64:65], v[60:61], v[68:69] op_sel_hi:[1,0]
	v_exp_f32_e32 v64, v64
	v_exp_f32_e32 v65, v65
	v_pk_mul_f32 v[62:63], v[62:63], v[68:69] op_sel_hi:[1,0]
	v_pk_add_f32 v[64:65], v[64:65], 1.0 op_sel_hi:[1,0]
	v_rcp_f32_e32 v64, v64
	v_rcp_f32_e32 v65, v65
	v_exp_f32_e32 v62, v62
	v_exp_f32_e32 v63, v63
	v_mul_f32_e32 v0, v0, v0
	v_pk_mul_f32 v[60:61], v[60:61], v[72:73]
	v_add_f32_e32 v62, 1.0, v62
	v_pk_mul_f32 v[60:61], v[60:61], v[0:1] op_sel_hi:[1,0]
	v_add_f32_e32 v63, 1.0, v63
	v_pk_mul_f32 v[60:61], v[60:61], v[64:65]
	v_pk_mul_f32 v[64:65], v[66:67], v[0:1] op_sel_hi:[1,0]
	v_pk_mul_f32 v[66:67], v[52:53], v[68:69] op_sel_hi:[1,0]
	v_rcp_f32_e32 v62, v62
	v_rcp_f32_e32 v63, v63
	v_exp_f32_e32 v66, v66
	v_exp_f32_e32 v67, v67
	v_pk_mul_f32 v[54:55], v[54:55], v[68:69] op_sel_hi:[1,0]
	v_exp_f32_e32 v54, v54
	v_exp_f32_e32 v55, v55
	v_pk_mul_f32 v[62:63], v[64:65], v[62:63]
	v_pk_add_f32 v[64:65], v[66:67], 1.0 op_sel_hi:[1,0]
	v_rcp_f32_e32 v64, v64
	v_rcp_f32_e32 v65, v65
	v_pk_add_f32 v[54:55], v[54:55], 1.0 op_sel_hi:[1,0]
	v_rcp_f32_e32 v54, v54
	v_rcp_f32_e32 v55, v55
	v_pk_mul_f32 v[52:53], v[52:53], v[56:57]
	s_nop 0
	v_pk_mul_f32 v[52:53], v[52:53], v[0:1] op_sel_hi:[1,0]
	s_nop 0
	v_pk_mul_f32 v[56:57], v[52:53], v[64:65]
	v_pk_mul_f32 v[52:53], v[58:59], v[0:1] op_sel_hi:[1,0]
	s_nop 0
	v_pk_mul_f32 v[58:59], v[52:53], v[54:55]
	v_cvt_pk_bf16_f32 v54, v56, v57
	v_add_co_u32_e32 v56, vcc, s12, v2
	v_cvt_pk_bf16_f32 v52, v60, v61
	v_cvt_pk_bf16_f32 v53, v62, v63
	v_cvt_pk_bf16_f32 v55, v58, v59
	v_addc_co_u32_e32 v57, vcc, 0, v3, vcc
	global_store_dwordx4 v[56:57], v[52:55], off
	ds_read_b32 v0, v142 offset:576
	s_mov_b32 s12, 0xd8000
	s_waitcnt lgkmcnt(0)
; __device__ __forceinline__ u32x4 pack8(const float (&v)[8]) { u32x4 w; w.x = pk2(v[0], v[1]); w.y = pk2(v[2], v[3]); w.z = pk2(v[4], v[5]); w.w = pk2(v[6], v[7]); return w; }
;     __device__ __forceinline__ bool operator()(Acc& acc, const Unit& u, int wr, int wc, int fr, int fq, const LAS float* rstab) const {
;     ...
; #pragma unroll
;         for (int ai = 0; ai < 2; ++ai)
; #pragma unroll
;             for (int m = 0; m < 4; ++m) {
;                 const float rs = rsp[ai * HALF + m * 16], nrs = -LOG2E * rs, rs2 = rs * rs;
;                 float v[8];
; #pragma unroll
;                 for (int n = 0; n < 2; ++n)
; #pragma unroll
;                     for (int e = 0; e < 4; ++e) {
;                         const float g = acc[ai][0][m][n][e], up = acc[ai][1][m][n][e];
;                         v[4 * n + e] = (g * up * rs2) * __builtin_amdgcn_rcpf(1.0f + __builtin_amdgcn_exp2f(g * nrs));
;                     }
;                 gst<u32x4>(p0 + (ai * HALF + m * 16) * HD_PITCH, pack8(v));
;                 asm volatile("" ::: "memory");
;             }
;         return true;
;     }
	v_mul_f32_e32 v54, 0xbfb8aa3b, v0
	v_pk_mul_f32 v[46:47], v[46:47], v[54:55] op_sel_hi:[1,0]
	v_exp_f32_e32 v46, v46
	v_exp_f32_e32 v47, v47
	v_mul_f32_e32 v0, v0, v0
	v_pk_mul_f32 v[52:53], v[44:45], v[54:55] op_sel_hi:[1,0]
	v_pk_mul_f32 v[44:45], v[44:45], v[48:49]
	v_pk_add_f32 v[46:47], v[46:47], 1.0 op_sel_hi:[1,0]
	v_pk_mul_f32 v[48:49], v[50:51], v[0:1] op_sel_hi:[1,0]
	v_pk_mul_f32 v[50:51], v[36:37], v[54:55] op_sel_hi:[1,0]
	v_rcp_f32_e32 v46, v46
	v_rcp_f32_e32 v47, v47
	v_exp_f32_e32 v50, v50
	v_exp_f32_e32 v51, v51
	v_pk_mul_f32 v[38:39], v[38:39], v[54:55] op_sel_hi:[1,0]
	v_exp_f32_e32 v52, v52
	v_exp_f32_e32 v53, v53
	v_exp_f32_e32 v38, v38
	v_exp_f32_e32 v39, v39
	v_pk_mul_f32 v[46:47], v[48:49], v[46:47]
	v_pk_add_f32 v[48:49], v[50:51], 1.0 op_sel_hi:[1,0]
	v_pk_add_f32 v[52:53], v[52:53], 1.0 op_sel_hi:[1,0]
	v_rcp_f32_e32 v48, v48
	v_rcp_f32_e32 v49, v49
	v_pk_add_f32 v[38:39], v[38:39], 1.0 op_sel_hi:[1,0]
	v_rcp_f32_e32 v52, v52
	v_rcp_f32_e32 v53, v53
	v_rcp_f32_e32 v38, v38
	v_rcp_f32_e32 v39, v39
	v_pk_mul_f32 v[36:37], v[36:37], v[40:41]
	v_pk_mul_f32 v[44:45], v[44:45], v[0:1] op_sel_hi:[1,0]
	v_pk_mul_f32 v[36:37], v[36:37], v[0:1] op_sel_hi:[1,0]
	v_pk_mul_f32 v[44:45], v[44:45], v[52:53]
	v_pk_mul_f32 v[40:41], v[36:37], v[48:49]
	v_pk_mul_f32 v[36:37], v[42:43], v[0:1] op_sel_hi:[1,0]
	s_nop 0
	v_pk_mul_f32 v[42:43], v[36:37], v[38:39]
	v_cvt_pk_bf16_f32 v38, v40, v41
	v_add_co_u32_e32 v40, vcc, s12, v2
	v_cvt_pk_bf16_f32 v36, v44, v45
	v_cvt_pk_bf16_f32 v37, v46, v47
	v_cvt_pk_bf16_f32 v39, v42, v43
	v_addc_co_u32_e32 v41, vcc, 0, v3, vcc
	global_store_dwordx4 v[40:41], v[36:39], off
	ds_read_b32 v0, v142 offset:640
	s_mov_b32 s12, 0xf0000
	s_waitcnt lgkmcnt(0)
	v_mul_f32_e32 v38, 0xbfb8aa3b, v0
	v_pk_mul_f32 v[30:31], v[30:31], v[38:39] op_sel_hi:[1,0]
	v_exp_f32_e32 v30, v30
	v_exp_f32_e32 v31, v31
	v_mul_f32_e32 v0, v0, v0
	v_pk_mul_f32 v[36:37], v[28:29], v[38:39] op_sel_hi:[1,0]
	v_pk_mul_f32 v[28:29], v[28:29], v[32:33]
	v_pk_add_f32 v[30:31], v[30:31], 1.0 op_sel_hi:[1,0]
	v_pk_mul_f32 v[32:33], v[34:35], v[0:1] op_sel_hi:[1,0]
	v_pk_mul_f32 v[34:35], v[20:21], v[38:39] op_sel_hi:[1,0]
	v_rcp_f32_e32 v30, v30
	v_rcp_f32_e32 v31, v31
	v_exp_f32_e32 v34, v34
	v_exp_f32_e32 v35, v35
	v_pk_mul_f32 v[22:23], v[22:23], v[38:39] op_sel_hi:[1,0]
	v_exp_f32_e32 v36, v36
	v_exp_f32_e32 v37, v37
	v_exp_f32_e32 v22, v22
	v_exp_f32_e32 v23, v23
	v_pk_mul_f32 v[30:31], v[32:33], v[30:31]
	v_pk_add_f32 v[32:33], v[34:35], 1.0 op_sel_hi:[1,0]
	v_pk_add_f32 v[36:37], v[36:37], 1.0 op_sel_hi:[1,0]
	v_rcp_f32_e32 v32, v32
	v_rcp_f32_e32 v33, v33
	v_pk_add_f32 v[22:23], v[22:23], 1.0 op_sel_hi:[1,0]
	v_rcp_f32_e32 v36, v36
	v_rcp_f32_e32 v37, v37
	v_rcp_f32_e32 v22, v22
	v_rcp_f32_e32 v23, v23
	v_pk_mul_f32 v[20:21], v[20:21], v[24:25]
	v_pk_mul_f32 v[28:29], v[28:29], v[0:1] op_sel_hi:[1,0]
	v_pk_mul_f32 v[20:21], v[20:21], v[0:1] op_sel_hi:[1,0]
	v_pk_mul_f32 v[28:29], v[28:29], v[36:37]
	v_pk_mul_f32 v[24:25], v[20:21], v[32:33]
	v_pk_mul_f32 v[20:21], v[26:27], v[0:1] op_sel_hi:[1,0]
	s_nop 0
	v_pk_mul_f32 v[26:27], v[20:21], v[22:23]
	v_cvt_pk_bf16_f32 v22, v24, v25
	v_add_co_u32_e32 v24, vcc, s12, v2
	v_cvt_pk_bf16_f32 v20, v28, v29
	v_cvt_pk_bf16_f32 v21, v30, v31
	v_cvt_pk_bf16_f32 v23, v26, v27
	v_addc_co_u32_e32 v25, vcc, 0, v3, vcc
	global_store_dwordx4 v[24:25], v[20:23], off
	ds_read_b32 v0, v142 offset:704
	v_add_co_u32_e32 v2, vcc, 0x108000, v2
	s_waitcnt lgkmcnt(0)
	v_mul_f32_e32 v22, 0xbfb8aa3b, v0
	v_pk_mul_f32 v[14:15], v[14:15], v[22:23] op_sel_hi:[1,0]
	v_exp_f32_e32 v14, v14
	v_exp_f32_e32 v15, v15
	v_mul_f32_e32 v0, v0, v0
	v_pk_mul_f32 v[20:21], v[12:13], v[22:23] op_sel_hi:[1,0]
	v_pk_mul_f32 v[12:13], v[12:13], v[16:17]
	v_pk_add_f32 v[14:15], v[14:15], 1.0 op_sel_hi:[1,0]
	v_pk_mul_f32 v[16:17], v[18:19], v[0:1] op_sel_hi:[1,0]
	v_pk_mul_f32 v[18:19], v[4:5], v[22:23] op_sel_hi:[1,0]
	v_rcp_f32_e32 v14, v14
	v_rcp_f32_e32 v15, v15
	v_exp_f32_e32 v18, v18
	v_exp_f32_e32 v19, v19
	v_pk_mul_f32 v[6:7], v[6:7], v[22:23] op_sel_hi:[1,0]
	v_exp_f32_e32 v20, v20
	v_exp_f32_e32 v21, v21
	v_exp_f32_e32 v6, v6
	v_exp_f32_e32 v7, v7
	v_pk_mul_f32 v[14:15], v[16:17], v[14:15]
	v_pk_add_f32 v[16:17], v[18:19], 1.0 op_sel_hi:[1,0]
	v_pk_add_f32 v[20:21], v[20:21], 1.0 op_sel_hi:[1,0]
	v_rcp_f32_e32 v16, v16
	v_rcp_f32_e32 v17, v17
	v_pk_add_f32 v[6:7], v[6:7], 1.0 op_sel_hi:[1,0]
	v_rcp_f32_e32 v20, v20
	v_rcp_f32_e32 v21, v21
	v_rcp_f32_e32 v6, v6
	v_rcp_f32_e32 v7, v7
	v_pk_mul_f32 v[4:5], v[4:5], v[8:9]
	v_pk_mul_f32 v[12:13], v[12:13], v[0:1] op_sel_hi:[1,0]
	v_pk_mul_f32 v[4:5], v[4:5], v[0:1] op_sel_hi:[1,0]
	v_pk_mul_f32 v[12:13], v[12:13], v[20:21]
	v_pk_mul_f32 v[8:9], v[4:5], v[16:17]
	v_pk_mul_f32 v[4:5], v[10:11], v[0:1] op_sel_hi:[1,0]
	v_addc_co_u32_e32 v3, vcc, 0, v3, vcc
	v_pk_mul_f32 v[10:11], v[4:5], v[6:7]
	v_cvt_pk_bf16_f32 v4, v12, v13
	v_cvt_pk_bf16_f32 v5, v14, v15
	v_cvt_pk_bf16_f32 v6, v8, v9
	v_cvt_pk_bf16_f32 v7, v10, v11
	global_store_dwordx4 v[2:3], v[4:7], off
	s_and_b64 vcc, exec, s[2:3]
	s_mov_b64 s[2:3], -1
	s_cbranch_vccnz .LBB0_1453
	v_mov_b32_e32 v225, v198
	v_mov_b64_e32 v[198:199], 0x5bf
	v_mov_b32_e32 v0, 1
	v_mov_b64_e32 v[226:227], 0x5c0
	v_mov_b64_e32 v[246:247], 0xff
	v_mov_b64_e32 v[244:245], 0x100
	s_and_b64 vcc, exec, s[0:1]
	s_cbranch_vccnz .LBB0_1452
	s_barrier
	s_branch .LBB0_1452
